# down-projection small_gemm: fragments loaded as 8 rows x 128 B per instruction (half the row segments) and transposed to MFMA layout through per-wave LDS
# speedup vs baseline: 1.0200x; 1.0066x over previous
.LBB0_338:
	s_ashr_i32 s0, s3, 31
	s_lshr_b32 s0, s0, 28
	s_add_i32 s0, s3, s0
	s_ashr_i32 s9, s0, 4
	s_lshl_b32 s8, s9, 5
	s_mul_i32 s0, s9, 0xffd40000
	s_addk_i32 s8, 0x4000
	v_add_u32_e32 v2, s0, v67
	v_or_b32_e32 v4, s8, v142
	v_ashrrev_i32_e32 v3, 31, v2
	v_mad_i64_i32 v[48:49], s[0:1], v4, s91, v[58:59]
	v_lshl_add_u64 v[46:47], v[2:3], 1, v[60:61]
	s_mov_b32 s0, 0x42000
	v_add_co_u32_e32 v50, vcc, s0, v46
	s_mov_b32 s0, 0x2c000
	v_add_co_u32_e64 v52, s[0:1], s0, v46
	v_add_co_u32_e64 v62, s[40:41], s7, v48
	s_nop 0
	v_addc_co_u32_e64 v53, s[0:1], 0, v47, s[0:1]
	v_addc_co_u32_e64 v63, s[0:1], 0, v49, s[40:41]
	v_add_co_u32_e64 v64, s[38:39], s7, v46
	v_addc_co_u32_e32 v51, vcc, 0, v47, vcc
	s_nop 0
	v_addc_co_u32_e64 v65, s[0:1], 0, v47, s[38:39]
	v_and_b32_e32 v250, 63, v204
	v_readfirstlane_b32 s98, v204
	s_lshr_b32 s98, s98, 6
	s_and_b32 s99, s98, 1
	s_mul_i32 s98, s98, 0x3600
	s_lshl_b32 s100, s99, 6
	v_and_b32_e32 v251, 15, v250
	v_lshrrev_b32_e32 v252, 4, v250
	v_mul_u32_u24_e32 v253, 0x90, v251
	v_lshl_add_u32 v253, v252, 4, v253
	v_add_u32_e32 v253, s98, v253
	v_lshrrev_b32_e32 v246, 3, v250
	v_and_b32_e32 v247, 7, v250
	v_sub_u32_e32 v248, v246, v251
	v_sub_u32_e32 v249, v247, v252
	s_movk_i32 s101, 0x1600
	v_mul_lo_u32 v248, v248, s101
	v_lshl_add_u32 v248, v249, 4, v248
	v_subrev_u32_e32 v248, s100, v248
	v_ashrrev_i32_e32 v249, 31, v248
	v_mul_u32_u24_e32 v252, 0x90, v246
	v_lshl_add_u32 v252, v247, 4, v252
	v_add_u32_e32 v252, s98, v252
	v_lshl_add_u64 v[34:35], v[48:49], 0, v[248:249]
	v_add_co_u32_e32 v36, vcc, 0xb000, v34
	s_nop 1
	v_addc_co_u32_e32 v37, vcc, 0, v35, vcc
	v_lshl_add_u64 v[38:39], v[62:63], 0, v[248:249]
	v_add_co_u32_e32 v40, vcc, 0xb000, v38
	s_nop 1
	v_addc_co_u32_e32 v41, vcc, 0, v39, vcc
	v_lshl_add_u64 v[42:43], v[46:47], 0, v[248:249]
	v_add_co_u32_e32 v44, vcc, 0xb000, v42
	s_nop 1
	v_addc_co_u32_e32 v45, vcc, 0, v43, vcc
	v_lshl_add_u64 v[54:55], v[64:65], 0, v[248:249]
	v_add_co_u32_e32 v56, vcc, 0xb000, v54
	s_nop 1
	v_addc_co_u32_e32 v57, vcc, 0, v55, vcc
	v_lshl_add_u64 v[70:71], v[52:53], 0, v[248:249]
	v_add_co_u32_e32 v72, vcc, 0xb000, v70
	s_nop 1
	v_addc_co_u32_e32 v73, vcc, 0, v71, vcc
	v_lshl_add_u64 v[186:187], v[50:51], 0, v[248:249]
	v_add_co_u32_e32 v162, vcc, 0xb000, v186
	s_nop 1
	v_addc_co_u32_e32 v163, vcc, 0, v187, vcc
	v_mov_b64_e32 v[18:19], 0
	v_mov_b64_e32 v[20:21], 0
	v_mov_b64_e32 v[26:27], 0
	v_mov_b64_e32 v[28:29], 0
	v_mov_b64_e32 v[14:15], 0
	v_mov_b64_e32 v[16:17], 0
	v_mov_b64_e32 v[10:11], 0
	v_mov_b64_e32 v[12:13], 0
	v_mov_b64_e32 v[6:7], 0
	v_mov_b64_e32 v[8:9], 0
	v_mov_b64_e32 v[2:3], 0
	v_mov_b64_e32 v[4:5], 0
	v_mov_b64_e32 v[30:31], 0
	v_mov_b64_e32 v[32:33], 0
	v_mov_b64_e32 v[22:23], 0
	v_mov_b64_e32 v[24:25], 0
	global_load_dwordx4 v[74:77], v[34:35], off
	global_load_dwordx4 v[78:81], v[36:37], off
	global_load_dwordx4 v[82:85], v[38:39], off
	global_load_dwordx4 v[86:89], v[40:41], off
	global_load_dwordx4 v[90:93], v[42:43], off
	global_load_dwordx4 v[94:97], v[44:45], off
	global_load_dwordx4 v[98:101], v[54:55], off
	global_load_dwordx4 v[102:105], v[56:57], off
	global_load_dwordx4 v[106:109], v[70:71], off
	global_load_dwordx4 v[110:113], v[72:73], off
	global_load_dwordx4 v[114:117], v[186:187], off
	global_load_dwordx4 v[118:121], v[162:163], off
	global_load_dwordx4 v[122:125], v[34:35], off offset:128
	global_load_dwordx4 v[126:129], v[36:37], off offset:128
	global_load_dwordx4 v[130:133], v[38:39], off offset:128
	global_load_dwordx4 v[134:137], v[40:41], off offset:128
	global_load_dwordx4 v[138:141], v[42:43], off offset:128
	global_load_dwordx4 v[166:169], v[44:45], off offset:128
	global_load_dwordx4 v[170:173], v[54:55], off offset:128
	global_load_dwordx4 v[174:177], v[56:57], off offset:128
	global_load_dwordx4 v[178:181], v[70:71], off offset:128
	global_load_dwordx4 v[182:185], v[72:73], off offset:128
	global_load_dwordx4 v[206:209], v[186:187], off offset:128
	global_load_dwordx4 v[210:213], v[162:163], off offset:128
	s_waitcnt vmcnt(12)
	s_barrier
	ds_write_b128 v252, v[74:77]
	ds_write_b128 v252, v[78:81] offset:1152
	ds_write_b128 v252, v[82:85] offset:2304
	ds_write_b128 v252, v[86:89] offset:3456
	ds_write_b128 v252, v[90:93] offset:4608
	ds_write_b128 v252, v[94:97] offset:5760
	ds_write_b128 v252, v[98:101] offset:6912
	ds_write_b128 v252, v[102:105] offset:8064
	ds_write_b128 v252, v[106:109] offset:9216
	ds_write_b128 v252, v[110:113] offset:10368
	ds_write_b128 v252, v[114:117] offset:11520
	ds_write_b128 v252, v[118:121] offset:12672
	ds_read_b128 v[74:77], v253
	ds_read_b128 v[82:85], v253 offset:2304
	ds_read_b128 v[90:93], v253 offset:4608
	ds_read_b128 v[98:101], v253 offset:6912
	ds_read_b128 v[106:109], v253 offset:9216
	ds_read_b128 v[114:117], v253 offset:11520
	ds_read_b128 v[78:81], v253 offset:64
	ds_read_b128 v[86:89], v253 offset:2368
	ds_read_b128 v[94:97], v253 offset:4672
	ds_read_b128 v[102:105], v253 offset:6976
	ds_read_b128 v[110:113], v253 offset:9280
	ds_read_b128 v[118:121], v253 offset:11584
	s_waitcnt lgkmcnt(6)
	s_cmp_lg_u32 s99, 0
	s_cbranch_scc1 .Lsgdn_skip_a
	v_mfma_f32_16x16x32_bf16 v[18:21], v[74:77], v[90:93], v[18:21]
	v_mfma_f32_16x16x32_bf16 v[26:29], v[74:77], v[98:101], v[26:29]
	v_mfma_f32_16x16x32_bf16 v[14:17], v[74:77], v[106:109], v[14:17]
	v_mfma_f32_16x16x32_bf16 v[10:13], v[74:77], v[114:117], v[10:13]
	v_mfma_f32_16x16x32_bf16 v[6:9], v[82:85], v[90:93], v[6:9]
	v_mfma_f32_16x16x32_bf16 v[2:5], v[82:85], v[98:101], v[2:5]
	v_mfma_f32_16x16x32_bf16 v[30:33], v[82:85], v[106:109], v[30:33]
	v_mfma_f32_16x16x32_bf16 v[22:25], v[82:85], v[114:117], v[22:25]
.Lsgdn_skip_a:
	s_waitcnt lgkmcnt(0)
	v_mfma_f32_16x16x32_bf16 v[18:21], v[78:81], v[94:97], v[18:21]
	v_mfma_f32_16x16x32_bf16 v[26:29], v[78:81], v[102:105], v[26:29]
	v_mfma_f32_16x16x32_bf16 v[14:17], v[78:81], v[110:113], v[14:17]
	v_mfma_f32_16x16x32_bf16 v[10:13], v[78:81], v[118:121], v[10:13]
	v_mfma_f32_16x16x32_bf16 v[6:9], v[86:89], v[94:97], v[6:9]
	v_mfma_f32_16x16x32_bf16 v[2:5], v[86:89], v[102:105], v[2:5]
	v_mfma_f32_16x16x32_bf16 v[30:33], v[86:89], v[110:113], v[30:33]
	v_mfma_f32_16x16x32_bf16 v[22:25], v[86:89], v[118:121], v[22:25]
	global_load_dwordx4 v[74:77], v[34:35], off offset:256
	global_load_dwordx4 v[78:81], v[36:37], off offset:256
	global_load_dwordx4 v[82:85], v[38:39], off offset:256
	global_load_dwordx4 v[86:89], v[40:41], off offset:256
	global_load_dwordx4 v[90:93], v[42:43], off offset:256
	global_load_dwordx4 v[94:97], v[44:45], off offset:256
	global_load_dwordx4 v[98:101], v[54:55], off offset:256
	global_load_dwordx4 v[102:105], v[56:57], off offset:256
	global_load_dwordx4 v[106:109], v[70:71], off offset:256
	global_load_dwordx4 v[110:113], v[72:73], off offset:256
	global_load_dwordx4 v[114:117], v[186:187], off offset:256
	global_load_dwordx4 v[118:121], v[162:163], off offset:256
	s_waitcnt vmcnt(12)
	ds_write_b128 v252, v[122:125]
	ds_write_b128 v252, v[126:129] offset:1152
	ds_write_b128 v252, v[130:133] offset:2304
	ds_write_b128 v252, v[134:137] offset:3456
	ds_write_b128 v252, v[138:141] offset:4608
	ds_write_b128 v252, v[166:169] offset:5760
	ds_write_b128 v252, v[170:173] offset:6912
	ds_write_b128 v252, v[174:177] offset:8064
	ds_write_b128 v252, v[178:181] offset:9216
	ds_write_b128 v252, v[182:185] offset:10368
	ds_write_b128 v252, v[206:209] offset:11520
	ds_write_b128 v252, v[210:213] offset:12672
	ds_read_b128 v[122:125], v253
	ds_read_b128 v[130:133], v253 offset:2304
	ds_read_b128 v[138:141], v253 offset:4608
	ds_read_b128 v[170:173], v253 offset:6912
	ds_read_b128 v[178:181], v253 offset:9216
	ds_read_b128 v[206:209], v253 offset:11520
	ds_read_b128 v[126:129], v253 offset:64
	ds_read_b128 v[134:137], v253 offset:2368
	ds_read_b128 v[166:169], v253 offset:4672
	ds_read_b128 v[174:177], v253 offset:6976
	ds_read_b128 v[182:185], v253 offset:9280
	ds_read_b128 v[210:213], v253 offset:11584
	s_waitcnt lgkmcnt(6)
	v_mfma_f32_16x16x32_bf16 v[18:21], v[122:125], v[138:141], v[18:21]
	v_mfma_f32_16x16x32_bf16 v[26:29], v[122:125], v[170:173], v[26:29]
	v_mfma_f32_16x16x32_bf16 v[14:17], v[122:125], v[178:181], v[14:17]
	v_mfma_f32_16x16x32_bf16 v[10:13], v[122:125], v[206:209], v[10:13]
	v_mfma_f32_16x16x32_bf16 v[6:9], v[130:133], v[138:141], v[6:9]
	v_mfma_f32_16x16x32_bf16 v[2:5], v[130:133], v[170:173], v[2:5]
	v_mfma_f32_16x16x32_bf16 v[30:33], v[130:133], v[178:181], v[30:33]
	v_mfma_f32_16x16x32_bf16 v[22:25], v[130:133], v[206:209], v[22:25]
	s_waitcnt lgkmcnt(0)
	v_mfma_f32_16x16x32_bf16 v[18:21], v[126:129], v[166:169], v[18:21]
	v_mfma_f32_16x16x32_bf16 v[26:29], v[126:129], v[174:177], v[26:29]
	v_mfma_f32_16x16x32_bf16 v[14:17], v[126:129], v[182:185], v[14:17]
	v_mfma_f32_16x16x32_bf16 v[10:13], v[126:129], v[210:213], v[10:13]
	v_mfma_f32_16x16x32_bf16 v[6:9], v[134:137], v[166:169], v[6:9]
	v_mfma_f32_16x16x32_bf16 v[2:5], v[134:137], v[174:177], v[2:5]
	v_mfma_f32_16x16x32_bf16 v[30:33], v[134:137], v[182:185], v[30:33]
	v_mfma_f32_16x16x32_bf16 v[22:25], v[134:137], v[210:213], v[22:25]
	global_load_dwordx4 v[122:125], v[34:35], off offset:384
	global_load_dwordx4 v[126:129], v[36:37], off offset:384
	global_load_dwordx4 v[130:133], v[38:39], off offset:384
	global_load_dwordx4 v[134:137], v[40:41], off offset:384
	global_load_dwordx4 v[138:141], v[42:43], off offset:384
	global_load_dwordx4 v[166:169], v[44:45], off offset:384
	global_load_dwordx4 v[170:173], v[54:55], off offset:384
	global_load_dwordx4 v[174:177], v[56:57], off offset:384
	global_load_dwordx4 v[178:181], v[70:71], off offset:384
	global_load_dwordx4 v[182:185], v[72:73], off offset:384
	global_load_dwordx4 v[206:209], v[186:187], off offset:384
	global_load_dwordx4 v[210:213], v[162:163], off offset:384
	s_waitcnt vmcnt(12)
	ds_write_b128 v252, v[74:77]
	ds_write_b128 v252, v[78:81] offset:1152
	ds_write_b128 v252, v[82:85] offset:2304
	ds_write_b128 v252, v[86:89] offset:3456
	ds_write_b128 v252, v[90:93] offset:4608
	ds_write_b128 v252, v[94:97] offset:5760
	ds_write_b128 v252, v[98:101] offset:6912
	ds_write_b128 v252, v[102:105] offset:8064
	ds_write_b128 v252, v[106:109] offset:9216
	ds_write_b128 v252, v[110:113] offset:10368
	ds_write_b128 v252, v[114:117] offset:11520
	ds_write_b128 v252, v[118:121] offset:12672
	ds_read_b128 v[74:77], v253
	ds_read_b128 v[82:85], v253 offset:2304
	ds_read_b128 v[90:93], v253 offset:4608
	ds_read_b128 v[98:101], v253 offset:6912
	ds_read_b128 v[106:109], v253 offset:9216
	ds_read_b128 v[114:117], v253 offset:11520
	ds_read_b128 v[78:81], v253 offset:64
	ds_read_b128 v[86:89], v253 offset:2368
	ds_read_b128 v[94:97], v253 offset:4672
	ds_read_b128 v[102:105], v253 offset:6976
	ds_read_b128 v[110:113], v253 offset:9280
	ds_read_b128 v[118:121], v253 offset:11584
	s_waitcnt lgkmcnt(6)
	v_mfma_f32_16x16x32_bf16 v[18:21], v[74:77], v[90:93], v[18:21]
	v_mfma_f32_16x16x32_bf16 v[26:29], v[74:77], v[98:101], v[26:29]
	v_mfma_f32_16x16x32_bf16 v[14:17], v[74:77], v[106:109], v[14:17]
	v_mfma_f32_16x16x32_bf16 v[10:13], v[74:77], v[114:117], v[10:13]
	v_mfma_f32_16x16x32_bf16 v[6:9], v[82:85], v[90:93], v[6:9]
	v_mfma_f32_16x16x32_bf16 v[2:5], v[82:85], v[98:101], v[2:5]
	v_mfma_f32_16x16x32_bf16 v[30:33], v[82:85], v[106:109], v[30:33]
	v_mfma_f32_16x16x32_bf16 v[22:25], v[82:85], v[114:117], v[22:25]
	s_waitcnt lgkmcnt(0)
	v_mfma_f32_16x16x32_bf16 v[18:21], v[78:81], v[94:97], v[18:21]
	v_mfma_f32_16x16x32_bf16 v[26:29], v[78:81], v[102:105], v[26:29]
	v_mfma_f32_16x16x32_bf16 v[14:17], v[78:81], v[110:113], v[14:17]
	v_mfma_f32_16x16x32_bf16 v[10:13], v[78:81], v[118:121], v[10:13]
	v_mfma_f32_16x16x32_bf16 v[6:9], v[86:89], v[94:97], v[6:9]
	v_mfma_f32_16x16x32_bf16 v[2:5], v[86:89], v[102:105], v[2:5]
	v_mfma_f32_16x16x32_bf16 v[30:33], v[86:89], v[110:113], v[30:33]
	v_mfma_f32_16x16x32_bf16 v[22:25], v[86:89], v[118:121], v[22:25]
	global_load_dwordx4 v[74:77], v[34:35], off offset:512
	global_load_dwordx4 v[78:81], v[36:37], off offset:512
	global_load_dwordx4 v[82:85], v[38:39], off offset:512
	global_load_dwordx4 v[86:89], v[40:41], off offset:512
	global_load_dwordx4 v[90:93], v[42:43], off offset:512
	global_load_dwordx4 v[94:97], v[44:45], off offset:512
	global_load_dwordx4 v[98:101], v[54:55], off offset:512
	global_load_dwordx4 v[102:105], v[56:57], off offset:512
	global_load_dwordx4 v[106:109], v[70:71], off offset:512
	global_load_dwordx4 v[110:113], v[72:73], off offset:512
	global_load_dwordx4 v[114:117], v[186:187], off offset:512
	global_load_dwordx4 v[118:121], v[162:163], off offset:512
	s_waitcnt vmcnt(12)
	ds_write_b128 v252, v[122:125]
	ds_write_b128 v252, v[126:129] offset:1152
	ds_write_b128 v252, v[130:133] offset:2304
	ds_write_b128 v252, v[134:137] offset:3456
	ds_write_b128 v252, v[138:141] offset:4608
	ds_write_b128 v252, v[166:169] offset:5760
	ds_write_b128 v252, v[170:173] offset:6912
	ds_write_b128 v252, v[174:177] offset:8064
	ds_write_b128 v252, v[178:181] offset:9216
	ds_write_b128 v252, v[182:185] offset:10368
	ds_write_b128 v252, v[206:209] offset:11520
	ds_write_b128 v252, v[210:213] offset:12672
	ds_read_b128 v[122:125], v253
	ds_read_b128 v[130:133], v253 offset:2304
	ds_read_b128 v[138:141], v253 offset:4608
	ds_read_b128 v[170:173], v253 offset:6912
	ds_read_b128 v[178:181], v253 offset:9216
	ds_read_b128 v[206:209], v253 offset:11520
	ds_read_b128 v[126:129], v253 offset:64
	ds_read_b128 v[134:137], v253 offset:2368
	ds_read_b128 v[166:169], v253 offset:4672
	ds_read_b128 v[174:177], v253 offset:6976
	ds_read_b128 v[182:185], v253 offset:9280
	ds_read_b128 v[210:213], v253 offset:11584
	s_waitcnt lgkmcnt(6)
	v_mfma_f32_16x16x32_bf16 v[18:21], v[122:125], v[138:141], v[18:21]
	v_mfma_f32_16x16x32_bf16 v[26:29], v[122:125], v[170:173], v[26:29]
	v_mfma_f32_16x16x32_bf16 v[14:17], v[122:125], v[178:181], v[14:17]
	v_mfma_f32_16x16x32_bf16 v[10:13], v[122:125], v[206:209], v[10:13]
	v_mfma_f32_16x16x32_bf16 v[6:9], v[130:133], v[138:141], v[6:9]
	v_mfma_f32_16x16x32_bf16 v[2:5], v[130:133], v[170:173], v[2:5]
	v_mfma_f32_16x16x32_bf16 v[30:33], v[130:133], v[178:181], v[30:33]
	v_mfma_f32_16x16x32_bf16 v[22:25], v[130:133], v[206:209], v[22:25]
	s_waitcnt lgkmcnt(0)
	v_mfma_f32_16x16x32_bf16 v[18:21], v[126:129], v[166:169], v[18:21]
	v_mfma_f32_16x16x32_bf16 v[26:29], v[126:129], v[174:177], v[26:29]
	v_mfma_f32_16x16x32_bf16 v[14:17], v[126:129], v[182:185], v[14:17]
	v_mfma_f32_16x16x32_bf16 v[10:13], v[126:129], v[210:213], v[10:13]
	v_mfma_f32_16x16x32_bf16 v[6:9], v[134:137], v[166:169], v[6:9]
	v_mfma_f32_16x16x32_bf16 v[2:5], v[134:137], v[174:177], v[2:5]
	v_mfma_f32_16x16x32_bf16 v[30:33], v[134:137], v[182:185], v[30:33]
	v_mfma_f32_16x16x32_bf16 v[22:25], v[134:137], v[210:213], v[22:25]
	global_load_dwordx4 v[122:125], v[34:35], off offset:640
	global_load_dwordx4 v[126:129], v[36:37], off offset:640
	global_load_dwordx4 v[130:133], v[38:39], off offset:640
	global_load_dwordx4 v[134:137], v[40:41], off offset:640
	global_load_dwordx4 v[138:141], v[42:43], off offset:640
	global_load_dwordx4 v[166:169], v[44:45], off offset:640
	global_load_dwordx4 v[170:173], v[54:55], off offset:640
	global_load_dwordx4 v[174:177], v[56:57], off offset:640
	global_load_dwordx4 v[178:181], v[70:71], off offset:640
	global_load_dwordx4 v[182:185], v[72:73], off offset:640
	global_load_dwordx4 v[206:209], v[186:187], off offset:640
	global_load_dwordx4 v[210:213], v[162:163], off offset:640
	s_waitcnt vmcnt(12)
	ds_write_b128 v252, v[74:77]
	ds_write_b128 v252, v[78:81] offset:1152
	ds_write_b128 v252, v[82:85] offset:2304
	ds_write_b128 v252, v[86:89] offset:3456
	ds_write_b128 v252, v[90:93] offset:4608
	ds_write_b128 v252, v[94:97] offset:5760
	ds_write_b128 v252, v[98:101] offset:6912
	ds_write_b128 v252, v[102:105] offset:8064
	ds_write_b128 v252, v[106:109] offset:9216
	ds_write_b128 v252, v[110:113] offset:10368
	ds_write_b128 v252, v[114:117] offset:11520
	ds_write_b128 v252, v[118:121] offset:12672
	ds_read_b128 v[74:77], v253
	ds_read_b128 v[82:85], v253 offset:2304
	ds_read_b128 v[90:93], v253 offset:4608
	ds_read_b128 v[98:101], v253 offset:6912
	ds_read_b128 v[106:109], v253 offset:9216
	ds_read_b128 v[114:117], v253 offset:11520
	ds_read_b128 v[78:81], v253 offset:64
	ds_read_b128 v[86:89], v253 offset:2368
	ds_read_b128 v[94:97], v253 offset:4672
	ds_read_b128 v[102:105], v253 offset:6976
	ds_read_b128 v[110:113], v253 offset:9280
	ds_read_b128 v[118:121], v253 offset:11584
	s_waitcnt lgkmcnt(6)
	v_mfma_f32_16x16x32_bf16 v[18:21], v[74:77], v[90:93], v[18:21]
	v_mfma_f32_16x16x32_bf16 v[26:29], v[74:77], v[98:101], v[26:29]
	v_mfma_f32_16x16x32_bf16 v[14:17], v[74:77], v[106:109], v[14:17]
	v_mfma_f32_16x16x32_bf16 v[10:13], v[74:77], v[114:117], v[10:13]
	v_mfma_f32_16x16x32_bf16 v[6:9], v[82:85], v[90:93], v[6:9]
	v_mfma_f32_16x16x32_bf16 v[2:5], v[82:85], v[98:101], v[2:5]
	v_mfma_f32_16x16x32_bf16 v[30:33], v[82:85], v[106:109], v[30:33]
	v_mfma_f32_16x16x32_bf16 v[22:25], v[82:85], v[114:117], v[22:25]
	s_waitcnt lgkmcnt(0)
	v_mfma_f32_16x16x32_bf16 v[18:21], v[78:81], v[94:97], v[18:21]
	v_mfma_f32_16x16x32_bf16 v[26:29], v[78:81], v[102:105], v[26:29]
	v_mfma_f32_16x16x32_bf16 v[14:17], v[78:81], v[110:113], v[14:17]
	v_mfma_f32_16x16x32_bf16 v[10:13], v[78:81], v[118:121], v[10:13]
	v_mfma_f32_16x16x32_bf16 v[6:9], v[86:89], v[94:97], v[6:9]
	v_mfma_f32_16x16x32_bf16 v[2:5], v[86:89], v[102:105], v[2:5]
	v_mfma_f32_16x16x32_bf16 v[30:33], v[86:89], v[110:113], v[30:33]
	v_mfma_f32_16x16x32_bf16 v[22:25], v[86:89], v[118:121], v[22:25]
	s_waitcnt vmcnt(0)
	ds_write_b128 v252, v[122:125]
	ds_write_b128 v252, v[126:129] offset:1152
	ds_write_b128 v252, v[130:133] offset:2304
	ds_write_b128 v252, v[134:137] offset:3456
	ds_write_b128 v252, v[138:141] offset:4608
	ds_write_b128 v252, v[166:169] offset:5760
	ds_write_b128 v252, v[170:173] offset:6912
	ds_write_b128 v252, v[174:177] offset:8064
	ds_write_b128 v252, v[178:181] offset:9216
	ds_write_b128 v252, v[182:185] offset:10368
	ds_write_b128 v252, v[206:209] offset:11520
	ds_write_b128 v252, v[210:213] offset:12672
	ds_read_b128 v[122:125], v253
	ds_read_b128 v[130:133], v253 offset:2304
	ds_read_b128 v[138:141], v253 offset:4608
	ds_read_b128 v[170:173], v253 offset:6912
	ds_read_b128 v[178:181], v253 offset:9216
	ds_read_b128 v[206:209], v253 offset:11520
	ds_read_b128 v[126:129], v253 offset:64
	ds_read_b128 v[134:137], v253 offset:2368
	ds_read_b128 v[166:169], v253 offset:4672
	ds_read_b128 v[174:177], v253 offset:6976
	ds_read_b128 v[182:185], v253 offset:9280
	ds_read_b128 v[210:213], v253 offset:11584
	s_waitcnt lgkmcnt(6)
	v_mfma_f32_16x16x32_bf16 v[18:21], v[122:125], v[138:141], v[18:21]
	v_mfma_f32_16x16x32_bf16 v[26:29], v[122:125], v[170:173], v[26:29]
	v_mfma_f32_16x16x32_bf16 v[14:17], v[122:125], v[178:181], v[14:17]
	v_mfma_f32_16x16x32_bf16 v[10:13], v[122:125], v[206:209], v[10:13]
	v_mfma_f32_16x16x32_bf16 v[6:9], v[130:133], v[138:141], v[6:9]
	v_mfma_f32_16x16x32_bf16 v[2:5], v[130:133], v[170:173], v[2:5]
	v_mfma_f32_16x16x32_bf16 v[30:33], v[130:133], v[178:181], v[30:33]
	v_mfma_f32_16x16x32_bf16 v[22:25], v[130:133], v[206:209], v[22:25]
	s_waitcnt lgkmcnt(0)
	s_cmp_eq_u32 s99, 0
	s_cbranch_scc1 .Lsgdn_skip_b
	v_mfma_f32_16x16x32_bf16 v[18:21], v[126:129], v[166:169], v[18:21]
	v_mfma_f32_16x16x32_bf16 v[26:29], v[126:129], v[174:177], v[26:29]
	v_mfma_f32_16x16x32_bf16 v[14:17], v[126:129], v[182:185], v[14:17]
	v_mfma_f32_16x16x32_bf16 v[10:13], v[126:129], v[210:213], v[10:13]
	v_mfma_f32_16x16x32_bf16 v[6:9], v[134:137], v[166:169], v[6:9]
	v_mfma_f32_16x16x32_bf16 v[2:5], v[134:137], v[174:177], v[2:5]
	v_mfma_f32_16x16x32_bf16 v[30:33], v[134:137], v[182:185], v[30:33]
	v_mfma_f32_16x16x32_bf16 v[22:25], v[134:137], v[210:213], v[22:25]
.Lsgdn_skip_b:
	s_waitcnt lgkmcnt(0)
	s_barrier
	s_nop 7
	s_nop 7
	s_lshl_b32 s0, s9, 10
	s_add_i32 s3, s3, s92
	s_cmpk_lt_i32 s3, 0x100
	v_add_u32_e32 v64, 0x1000, v68
	v_add_u32_e32 v65, 0x1400, v68
	v_subrev_u32_e32 v62, s0, v66
	s_mul_i32 s0, s92, 0x2c000
	v_ashrrev_i32_e32 v63, 31, v62
	v_add_u32_e32 v66, s2, v66
	v_add_u32_e32 v67, s0, v67
	v_add_u32_e32 v46, s8, v0
	v_ashrrev_i32_e32 v47, 31, v46
	v_lshlrev_b64 v[42:43], 11, v[46:47]
	v_lshl_add_u64 v[42:43], s[20:21], 0, v[42:43]
	v_lshl_add_u64 v[42:43], v[62:63], 1, v[42:43]
	ds_write2_b32 v68, v18, v26 offset1:16
	ds_write2_b32 v68, v19, v27 offset0:68 offset1:84
	ds_write2_b32 v68, v20, v28 offset0:136 offset1:152
	ds_write2_b32 v68, v21, v29 offset0:204 offset1:220
	ds_write2_b32 v68, v14, v10 offset0:32 offset1:48
	ds_write2_b32 v68, v15, v11 offset0:100 offset1:116
	ds_write2_b32 v68, v16, v12 offset0:168 offset1:184
	ds_write2_b32 v68, v17, v13 offset0:236 offset1:252
	ds_write2_b32 v64, v6, v2 offset0:64 offset1:80
	ds_write2_b32 v64, v7, v3 offset0:132 offset1:148
	ds_write2_b32 v64, v8, v4 offset0:200 offset1:216
	ds_write2_b32 v65, v9, v5 offset0:12 offset1:28
	ds_write2_b32 v64, v30, v22 offset0:96 offset1:112
	ds_write2_b32 v64, v31, v23 offset0:164 offset1:180
	ds_write2_b32 v64, v32, v24 offset0:232 offset1:248
	ds_write2_b32 v65, v33, v25 offset0:44 offset1:60
	s_waitcnt lgkmcnt(0)
	s_barrier
	ds_read_b128 v[2:5], v69
	ds_read_b128 v[6:9], v69 offset:8704
	ds_read_b128 v[10:13], v69 offset:17408
	ds_read_b128 v[14:17], v69 offset:26112
	ds_read_b128 v[18:21], v69 offset:34816
	ds_read_b128 v[22:25], v69 offset:43520
	ds_read_b128 v[26:29], v69 offset:52224
	ds_read_b128 v[30:33], v69 offset:60928
	s_waitcnt lgkmcnt(7)
	v_pk_add_f32 v[2:3], v[2:3], 0 op_sel_hi:[1,0]
	v_pk_add_f32 v[4:5], v[4:5], 0 op_sel_hi:[1,0]
	s_waitcnt lgkmcnt(6)
	v_pk_add_f32 v[2:3], v[2:3], v[6:7]
	v_pk_add_f32 v[4:5], v[4:5], v[8:9]
	s_waitcnt lgkmcnt(5)
	v_pk_add_f32 v[2:3], v[2:3], v[10:11]
	v_pk_add_f32 v[4:5], v[4:5], v[12:13]
	s_waitcnt lgkmcnt(4)
	v_pk_add_f32 v[2:3], v[2:3], v[14:15]
	v_pk_add_f32 v[4:5], v[4:5], v[16:17]
	s_waitcnt lgkmcnt(3)
	v_pk_add_f32 v[2:3], v[2:3], v[18:19]
	v_pk_add_f32 v[4:5], v[4:5], v[20:21]
	s_waitcnt lgkmcnt(2)
	v_pk_add_f32 v[2:3], v[2:3], v[22:23]
	v_pk_add_f32 v[4:5], v[4:5], v[24:25]
	s_waitcnt lgkmcnt(1)
	v_pk_add_f32 v[2:3], v[2:3], v[26:27]
	v_pk_add_f32 v[4:5], v[4:5], v[28:29]
	s_waitcnt lgkmcnt(0)
	v_pk_add_f32 v[2:3], v[2:3], v[30:31]
	v_pk_add_f32 v[4:5], v[4:5], v[32:33]
	v_pk_add_f32 v[2:3], v[2:3], 0 op_sel_hi:[1,0]
	v_pk_add_f32 v[4:5], v[4:5], 0 op_sel_hi:[1,0]
	v_cvt_pk_bf16_f32 v2, v2, v3
	s_nop 0
	v_cvt_pk_bf16_f32 v3, v4, v5
	global_store_dwordx2 v[42:43], v[2:3], off
	s_cbranch_scc1 .LBB0_338
